# attention epilogue: next-ticket atomic and subln gain load issued at loop exit, consumed after the first epilogue barrier
# baseline (speedup 1.0000x reference)
.LBB0_1402:
	v_cmp_eq_u32_e64 s[0:1], 0, v192
	v_cmp_gt_i32_e32 vcc, s40, v192
	s_and_saveexec_b64 s[6:7], vcc
	s_cbranch_execz .Lepi_nosgl
	v_readlane_b32 s60, v244, 44
	v_readlane_b32 s61, v244, 45
	s_nop 3
	v_lshl_add_u64 v[254:255], v[192:193], 2, s[60:61]
	global_load_dword v247, v[254:255], off
.Lepi_nosgl:
	s_or_b64 exec, exec, s[6:7]
	s_and_saveexec_b64 s[6:7], s[0:1]
	s_cbranch_execz .LBB0_1406
	v_mov_b32_e32 v253, 1
	global_atomic_add v253, v189, v253, s[8:9] sc0

.LBB0_1411:
	v_cmp_gt_i32_e32 vcc, s40, v192
	s_and_saveexec_b64 s[4:5], vcc
	s_cbranch_execz .LBB0_1413
	v_readlane_b32 s52, v244, 36
	v_readlane_b32 s60, v244, 44
	v_readlane_b32 s61, v244, 45
	v_readlane_b32 s53, v244, 37
	v_readlane_b32 s54, v244, 38
	v_lshl_add_u32 v85, v192, 2, 0
	v_add_u32_e32 v85, 0x18800, v85
	v_readlane_b32 s55, v244, 39
	v_readlane_b32 s56, v244, 40
	v_readlane_b32 s57, v244, 41
	v_readlane_b32 s58, v244, 42
	v_readlane_b32 s59, v244, 43
	v_readlane_b32 s62, v244, 46
	v_readlane_b32 s63, v244, 47
	v_readlane_b32 s64, v244, 48
	v_readlane_b32 s65, v244, 49
	v_readlane_b32 s66, v244, 50
	v_readlane_b32 s67, v244, 51
	s_cmp_lg_u64 s[0:1], 0
	s_cbranch_scc1 .Lepi_w0
	s_waitcnt vmcnt(0)
	s_branch .Lepi_w1
.Lepi_w0:
	s_waitcnt vmcnt(1)
.Lepi_w1:
	ds_write_b32 v85, v247

.LBB0_1416:
	s_and_saveexec_b64 s[4:5], s[0:1]
	s_cbranch_execz .LBB0_1312
	v_mov_b32_e32 v2, s3
	ds_write_b32 v2, v253
	s_branch .LBB0_1312
	s_nop 0
	s_nop 0

	.amdhsa_kernel _Z14fwd_megakernel6Params
		.amdhsa_group_segment_fixed_size 0
		.amdhsa_private_segment_fixed_size 0
		.amdhsa_kernarg_size 536
		.amdhsa_user_sgpr_count 2
		.amdhsa_user_sgpr_dispatch_ptr 0
		.amdhsa_user_sgpr_queue_ptr 0
		.amdhsa_user_sgpr_kernarg_segment_ptr 1
		.amdhsa_user_sgpr_dispatch_id 0
		.amdhsa_user_sgpr_kernarg_preload_length 0
		.amdhsa_user_sgpr_kernarg_preload_offset 0
		.amdhsa_user_sgpr_private_segment_size 0
		.amdhsa_uses_dynamic_stack 0
		.amdhsa_enable_private_segment 0
		.amdhsa_system_sgpr_workgroup_id_x 1
		.amdhsa_system_sgpr_workgroup_id_y 0
		.amdhsa_system_sgpr_workgroup_id_z 0
		.amdhsa_system_sgpr_workgroup_info 0
		.amdhsa_system_vgpr_workitem_id 0
		.amdhsa_next_free_vgpr 256
		.amdhsa_next_free_sgpr 100
		.amdhsa_accum_offset 256
		.amdhsa_reserve_vcc 1
		.amdhsa_float_round_mode_32 0
		.amdhsa_float_round_mode_16_64 0
		.amdhsa_float_denorm_mode_32 3
		.amdhsa_float_denorm_mode_16_64 3
		.amdhsa_dx10_clamp 1
		.amdhsa_ieee_mode 1
		.amdhsa_fp16_overflow 0
		.amdhsa_tg_split 0
		.amdhsa_exception_fp_ieee_invalid_op 0
		.amdhsa_exception_fp_denorm_src 0
		.amdhsa_exception_fp_ieee_div_zero 0
		.amdhsa_exception_fp_ieee_overflow 0
		.amdhsa_exception_fp_ieee_underflow 0
		.amdhsa_exception_fp_ieee_inexact 0
		.amdhsa_exception_int_div_zero 0
	.end_amdhsa_kernel

amdhsa.kernels:
  - .agpr_count:     0
    .args:
      - .offset:         0
        .size:           280
        .value_kind:     by_value
      - .offset:         280
        .size:           4
        .value_kind:     hidden_block_count_x
      - .offset:         284
        .size:           4
        .value_kind:     hidden_block_count_y
      - .offset:         288
        .size:           4
        .value_kind:     hidden_block_count_z
      - .offset:         292
        .size:           2
        .value_kind:     hidden_group_size_x
      - .offset:         294
        .size:           2
        .value_kind:     hidden_group_size_y
      - .offset:         296
        .size:           2
        .value_kind:     hidden_group_size_z
      - .offset:         298
        .size:           2
        .value_kind:     hidden_remainder_x
      - .offset:         300
        .size:           2
        .value_kind:     hidden_remainder_y
      - .offset:         302
        .size:           2
        .value_kind:     hidden_remainder_z
      - .offset:         320
        .size:           8
        .value_kind:     hidden_global_offset_x
      - .offset:         328
        .size:           8
        .value_kind:     hidden_global_offset_y
      - .offset:         336
        .size:           8
        .value_kind:     hidden_global_offset_z
      - .offset:         344
        .size:           2
        .value_kind:     hidden_grid_dims
      - .offset:         400
        .size:           4
        .value_kind:     hidden_dynamic_lds_size
    .group_segment_fixed_size: 0
    .kernarg_segment_align: 8
    .kernarg_segment_size: 536
    .language:       OpenCL C
    .language_version:
      - 2
      - 0
    .max_flat_workgroup_size: 512
    .name:           _Z14fwd_megakernel6Params
    .private_segment_fixed_size: 0
    .sgpr_count:     106
    .sgpr_spill_count: 56
    .symbol:         _Z14fwd_megakernel6Params.kd
    .uniform_work_group_size: 1
    .uses_dynamic_stack: false
    .vgpr_count:     256
    .vgpr_spill_count: 0
    .wavefront_size: 64
